# e19: out_proj epilogue re-staged 3+5 row-blocks: stage-0 counter bumped at row-block 5 and polled behind the last x load, stage 0 stored right after the x stream while stage 1's sums travel
# baseline (speedup 1.0000x reference)
;     __device__ __forceinline__ void operator()(AccRef acc, const Unit& u, int wr, int wc, int fr, int fq) const {
;         int row0 = u.pm * 256 + wr * 64 + fr; asm volatile("" : "+v"(row0)); int col0 = u.pn * 256 + wc * 32 + 8 * fq; asm volatile("" : "+v"(col0));
;         const float* gate = mod + (size_t)(u.pm >= 32 ? 1 : 0) * 3 * D + 2 * D + col0;
;         f32x4 gv[2][2];
; #pragma unroll
;         for (int bj = 0; bj < 2; ++bj)
; #pragma unroll
;             for (int n = 0; n < 2; ++n) gv[bj][n] = *(const f32x4*)(gate + bj * HALF + n * 4);
; #pragma unroll
;         for (int ai = 0; ai < 2; ++ai)
; #pragma unroll
;             for (int mp = 0; mp < 2; ++mp) { f32x4 xv[2][2][2];
; #pragma unroll
;                 for (int mm = 0; mm < 2; ++mm)
; #pragma unroll
;                     for (int bj = 0; bj < 2; ++bj)
; #pragma unroll
;                         for (int n = 0; n < 2; ++n) xv[mm][bj][n] = ld_nt(x + (size_t)(row0 + ai * HALF + (mp * 2 + mm) * 16) * D + col0 + bj * HALF + n * 4);
;                 __builtin_amdgcn_sched_barrier(0);
; #pragma unroll
;                 for (int mm = 0; mm < 2; ++mm) { const int m = mp * 2 + mm; const int row = row0 + ai * HALF + m * 16; const size_t o = (size_t)row * D + col0; float ss = 0.f;
; #pragma unroll
;                     for (int bj = 0; bj < 2; ++bj) { const f32x4 r0 = xv[mm][bj][0] + gv[bj][0] * acc[ai][bj][m][0], r1 = xv[mm][bj][1] + gv[bj][1] * acc[ai][bj][m][1];
;                         *(u32x4*)(xo + o + bj * HALF) = pack8h(r0, r1);
;                         ss += ((r0[0] * r0[0] + r0[1] * r0[1]) + (r0[2] * r0[2] + r0[3] * r0[3])) + ((r1[0] * r1[0] + r1[1] * r1[1]) + (r1[2] * r1[2] + r1[3] * r1[3])); }
;                     ss += __shfl_xor(ss, 16); ss += __shfl_xor(ss, 32);
;                     if (fq == 0) rowss[(size_t)row * 32 + u.pn * 4 + wc] = ss; } }
; __device__ __forceinline__ void final_rows(int gw, int lane, const f16* xo, float* out, const float* fg, const float* rowss) {
;     ...
;         for (int rr = 0; rr < 4; ++rr) { part[rr] = lane < 32 ? rowss[(size_t)(r0 + rr) * 32 + lane] : 0.f;
; #pragma unroll
;             for (int j = 0; j < 4; ++j) v[rr][j] = *(const u32x4*)(xo + (size_t)(r0 + rr) * D + 512 * j + 8 * lane); }
;         __builtin_amdgcn_sched_barrier(0);
; #pragma unroll
.LBB0_1154:
	v_lshl_add_u32 v172, s58, 8, v178
	v_lshl_or_b32 v170, s22, 8, v180
	v_readlane_b32 s80, v254, 2
	v_readlane_b32 s81, v254, 3
	v_lshlrev_b32_e32 v173, 13, v172
	v_lshlrev_b32_e32 v187, 7, v172
	v_lshlrev_b32_e32 v171, 2, v170
	v_lshl_add_u32 v173, v170, 2, v173
	s_lshl_b32 s18, s22, 2
	s_add_u32 s18, s18, s72
	s_lshl_b32 s18, s18, 2
	s_add_u32 s88, s26, s18
	s_addc_u32 s89, s27, 0
	v_xor_b32_e32 v186, 16, v184
	v_xor_b32_e32 v185, 32, v184
	v_lshrrev_b32_e32 v174, 4, v184
	v_lshlrev_b32_e32 v186, 2, v186
	v_lshlrev_b32_e32 v185, 2, v185
	v_lshl_add_u32 v174, v174, 5, v187
	s_mov_b32 s94, 0x3a000000
	s_mov_b32 s95, 0x358637bd
	s_mov_b64 s[82:83], s[48:49]
	s_lshr_b32 s59, s65, 10
	global_load_dwordx4 v[144:147], v171, s[46:47]
	global_load_dwordx4 v[148:151], v171, s[46:47] offset:16
	global_load_dwordx4 v[152:155], v171, s[46:47] offset:512
	global_load_dwordx4 v[156:159], v171, s[46:47] offset:528
	s_add_u32 s84, s80, 0x20000
	s_addc_u32 s85, s81, 0
	global_load_dwordx4 v[188:191], v173, s[84:85] nt
	global_load_dwordx4 v[192:195], v173, s[84:85] offset:16 nt
	global_load_dwordx4 v[196:199], v173, s[84:85] offset:512 nt
	global_load_dwordx4 v[200:203], v173, s[84:85] offset:528 nt
	s_add_u32 s84, s80, 0x40000
	s_addc_u32 s85, s81, 0
	global_load_dwordx4 v[104:107], v173, s[84:85] nt
	global_load_dwordx4 v[108:111], v173, s[84:85] offset:16 nt
	global_load_dwordx4 v[112:115], v173, s[84:85] offset:512 nt
	global_load_dwordx4 v[120:123], v173, s[84:85] offset:528 nt
	s_waitcnt vmcnt(12)
	v_pk_fma_f32 v[140:141], v[140:141], v[218:219], v[234:235]
	v_pk_fma_f32 v[142:143], v[142:143], v[220:221], v[236:237]
	v_pk_fma_f32 v[136:137], v[136:137], v[222:223], v[238:239]
	v_pk_fma_f32 v[138:139], v[138:139], v[224:225], v[240:241]
	v_pk_fma_f32 v[132:133], v[132:133], v[226:227], v[242:243]
	v_pk_fma_f32 v[134:135], v[134:135], v[228:229], v[244:245]
	v_pk_fma_f32 v[128:129], v[128:129], v[230:231], v[246:247]
	v_pk_fma_f32 v[130:131], v[130:131], v[232:233], v[248:249]
	s_add_u32 s84, s80, 0x60000
	s_addc_u32 s85, s81, 0
	global_load_dwordx4 v[234:237], v173, s[84:85] nt
	global_load_dwordx4 v[238:241], v173, s[84:85] offset:16 nt
	global_load_dwordx4 v[242:245], v173, s[84:85] offset:512 nt
	global_load_dwordx4 v[246:249], v173, s[84:85] offset:528 nt
	v_pk_mul_f32 v[176:177], v[140:141], v[140:141]
	v_pk_fma_f32 v[176:177], v[142:143], v[142:143], v[176:177]
	v_pk_fma_f32 v[176:177], v[136:137], v[136:137], v[176:177]
	v_pk_fma_f32 v[176:177], v[138:139], v[138:139], v[176:177]
	v_pk_fma_f32 v[176:177], v[132:133], v[132:133], v[176:177]
	v_pk_fma_f32 v[176:177], v[134:135], v[134:135], v[176:177]
	v_pk_fma_f32 v[176:177], v[128:129], v[128:129], v[176:177]
	v_pk_fma_f32 v[176:177], v[130:131], v[130:131], v[176:177]
	v_add_f32_e32 v204, v176, v177
	s_waitcnt vmcnt(8)
	v_pk_fma_f32 v[124:125], v[124:125], v[218:219], v[188:189]
	v_pk_fma_f32 v[126:127], v[126:127], v[220:221], v[190:191]
	v_pk_fma_f32 v[116:117], v[116:117], v[222:223], v[192:193]
	v_pk_fma_f32 v[118:119], v[118:119], v[224:225], v[194:195]
	v_pk_fma_f32 v[100:101], v[100:101], v[226:227], v[196:197]
	v_pk_fma_f32 v[102:103], v[102:103], v[228:229], v[198:199]
	v_pk_fma_f32 v[96:97], v[96:97], v[230:231], v[200:201]
	v_pk_fma_f32 v[98:99], v[98:99], v[232:233], v[202:203]
	s_add_u32 s84, s80, 0x100000
	s_addc_u32 s85, s81, 0
	global_load_dwordx4 v[188:191], v173, s[84:85] nt
	global_load_dwordx4 v[192:195], v173, s[84:85] offset:16 nt
	global_load_dwordx4 v[196:199], v173, s[84:85] offset:512 nt
	global_load_dwordx4 v[200:203], v173, s[84:85] offset:528 nt
	v_pk_mul_f32 v[176:177], v[124:125], v[124:125]
	v_pk_fma_f32 v[176:177], v[126:127], v[126:127], v[176:177]
	v_pk_fma_f32 v[176:177], v[116:117], v[116:117], v[176:177]
	v_pk_fma_f32 v[176:177], v[118:119], v[118:119], v[176:177]
	v_pk_fma_f32 v[176:177], v[100:101], v[100:101], v[176:177]
	v_pk_fma_f32 v[176:177], v[102:103], v[102:103], v[176:177]
	v_pk_fma_f32 v[176:177], v[96:97], v[96:97], v[176:177]
	v_pk_fma_f32 v[176:177], v[98:99], v[98:99], v[176:177]
	v_add_f32_e32 v205, v176, v177
	s_waitcnt vmcnt(8)
	v_pk_fma_f32 v[92:93], v[92:93], v[218:219], v[104:105]
	v_pk_fma_f32 v[94:95], v[94:95], v[220:221], v[106:107]
	v_pk_fma_f32 v[88:89], v[88:89], v[222:223], v[108:109]
	v_pk_fma_f32 v[90:91], v[90:91], v[224:225], v[110:111]
	v_pk_fma_f32 v[84:85], v[84:85], v[226:227], v[112:113]
	v_pk_fma_f32 v[86:87], v[86:87], v[228:229], v[114:115]
	v_pk_fma_f32 v[80:81], v[80:81], v[230:231], v[120:121]
	v_pk_fma_f32 v[82:83], v[82:83], v[232:233], v[122:123]
	s_add_u32 s84, s80, 0x120000
	s_addc_u32 s85, s81, 0
	global_load_dwordx4 v[104:107], v173, s[84:85] nt
	global_load_dwordx4 v[108:111], v173, s[84:85] offset:16 nt
	global_load_dwordx4 v[112:115], v173, s[84:85] offset:512 nt
	global_load_dwordx4 v[120:123], v173, s[84:85] offset:528 nt
	v_pk_mul_f32 v[176:177], v[92:93], v[92:93]
	v_pk_fma_f32 v[176:177], v[94:95], v[94:95], v[176:177]
	v_pk_fma_f32 v[176:177], v[88:89], v[88:89], v[176:177]
	v_pk_fma_f32 v[176:177], v[90:91], v[90:91], v[176:177]
	v_pk_fma_f32 v[176:177], v[84:85], v[84:85], v[176:177]
	v_pk_fma_f32 v[176:177], v[86:87], v[86:87], v[176:177]
	v_pk_fma_f32 v[176:177], v[80:81], v[80:81], v[176:177]
	v_pk_fma_f32 v[176:177], v[82:83], v[82:83], v[176:177]
	v_add_f32_e32 v206, v176, v177
	ds_bpermute_b32 v214, v186, v204
	ds_bpermute_b32 v215, v186, v205
	ds_bpermute_b32 v216, v186, v206
	s_waitcnt lgkmcnt(0)
	v_add_f32_e32 v204, v204, v214
	v_add_f32_e32 v205, v205, v215
	v_add_f32_e32 v206, v206, v216
	ds_bpermute_b32 v214, v185, v204
	ds_bpermute_b32 v215, v185, v205
	ds_bpermute_b32 v216, v185, v206
	s_waitcnt lgkmcnt(0)
;     __device__ __forceinline__ void operator()(AccRef acc, const Unit& u, int wr, int wc, int fr, int fq) const {
;         int row0 = u.pm * 256 + wr * 64 + fr; asm volatile("" : "+v"(row0)); int col0 = u.pn * 256 + wc * 32 + 8 * fq; asm volatile("" : "+v"(col0));
;         const float* gate = mod + (size_t)(u.pm >= 32 ? 1 : 0) * 3 * D + 2 * D + col0;
;         f32x4 gv[2][2];
; #pragma unroll
;         for (int bj = 0; bj < 2; ++bj)
; #pragma unroll
;             for (int n = 0; n < 2; ++n) gv[bj][n] = *(const f32x4*)(gate + bj * HALF + n * 4);
; #pragma unroll
;         for (int ai = 0; ai < 2; ++ai)
; #pragma unroll
;             for (int mp = 0; mp < 2; ++mp) { f32x4 xv[2][2][2];
; #pragma unroll
;                 for (int mm = 0; mm < 2; ++mm)
; #pragma unroll
;                     for (int bj = 0; bj < 2; ++bj)
; #pragma unroll
;                         for (int n = 0; n < 2; ++n) xv[mm][bj][n] = ld_nt(x + (size_t)(row0 + ai * HALF + (mp * 2 + mm) * 16) * D + col0 + bj * HALF + n * 4);
;                 __builtin_amdgcn_sched_barrier(0);
; #pragma unroll
;                 for (int mm = 0; mm < 2; ++mm) { const int m = mp * 2 + mm; const int row = row0 + ai * HALF + m * 16; const size_t o = (size_t)row * D + col0; float ss = 0.f;
; #pragma unroll
;                     for (int bj = 0; bj < 2; ++bj) { const f32x4 r0 = xv[mm][bj][0] + gv[bj][0] * acc[ai][bj][m][0], r1 = xv[mm][bj][1] + gv[bj][1] * acc[ai][bj][m][1];
;                         *(u32x4*)(xo + o + bj * HALF) = pack8h(r0, r1);
;                         ss += ((r0[0] * r0[0] + r0[1] * r0[1]) + (r0[2] * r0[2] + r0[3] * r0[3])) + ((r1[0] * r1[0] + r1[1] * r1[1]) + (r1[2] * r1[2] + r1[3] * r1[3])); }
;                     ss += __shfl_xor(ss, 16); ss += __shfl_xor(ss, 32);
;                     if (fq == 0) rowss[(size_t)row * 32 + u.pn * 4 + wc] = ss; } }
; __device__ __forceinline__ void final_rows(int gw, int lane, const f16* xo, float* out, const float* fg, const float* rowss) {
;     ...
;         for (int rr = 0; rr < 4; ++rr) { part[rr] = lane < 32 ? rowss[(size_t)(r0 + rr) * 32 + lane] : 0.f;
; #pragma unroll
;             for (int j = 0; j < 4; ++j) v[rr][j] = *(const u32x4*)(xo + (size_t)(r0 + rr) * D + 512 * j + 8 * lane); }
;         __builtin_amdgcn_sched_barrier(0);
; #pragma unroll
	v_add_f32_e32 v204, v204, v214
	v_add_f32_e32 v205, v205, v215
	v_add_f32_e32 v206, v206, v216
	s_and_saveexec_b64 s[20:21], s[2:3]
	s_mov_b64 s[90:91], s[88:89]
	global_store_dword v187, v204, s[90:91] sc0 sc1
	s_add_u32 s90, s88, 0x800
	s_addc_u32 s91, s89, 0
	global_store_dword v187, v205, s[90:91] sc0 sc1
	s_add_u32 s90, s88, 0x1000
	s_addc_u32 s91, s89, 0
	global_store_dword v187, v206, s[90:91] sc0 sc1
	s_or_b64 exec, exec, s[20:21]
	s_waitcnt vmcnt(11)
	v_pk_fma_f32 v[76:77], v[76:77], v[218:219], v[234:235]
	v_pk_fma_f32 v[78:79], v[78:79], v[220:221], v[236:237]
	v_pk_fma_f32 v[72:73], v[72:73], v[222:223], v[238:239]
	v_pk_fma_f32 v[74:75], v[74:75], v[224:225], v[240:241]
	v_pk_fma_f32 v[68:69], v[68:69], v[226:227], v[242:243]
	v_pk_fma_f32 v[70:71], v[70:71], v[228:229], v[244:245]
	v_pk_fma_f32 v[64:65], v[64:65], v[230:231], v[246:247]
	v_pk_fma_f32 v[66:67], v[66:67], v[232:233], v[248:249]
	s_add_u32 s84, s80, 0x140000
	s_addc_u32 s85, s81, 0
	global_load_dwordx4 v[234:237], v173, s[84:85] nt
	global_load_dwordx4 v[238:241], v173, s[84:85] offset:16 nt
	global_load_dwordx4 v[242:245], v173, s[84:85] offset:512 nt
	global_load_dwordx4 v[246:249], v173, s[84:85] offset:528 nt
	v_pk_mul_f32 v[176:177], v[76:77], v[76:77]
	v_pk_fma_f32 v[176:177], v[78:79], v[78:79], v[176:177]
	v_pk_fma_f32 v[176:177], v[72:73], v[72:73], v[176:177]
	v_pk_fma_f32 v[176:177], v[74:75], v[74:75], v[176:177]
	v_pk_fma_f32 v[176:177], v[68:69], v[68:69], v[176:177]
	v_pk_fma_f32 v[176:177], v[70:71], v[70:71], v[176:177]
	v_pk_fma_f32 v[176:177], v[64:65], v[64:65], v[176:177]
	v_pk_fma_f32 v[176:177], v[66:67], v[66:67], v[176:177]
	v_add_f32_e32 v207, v176, v177
	s_waitcnt vmcnt(11)
	v_pk_fma_f32 v[60:61], v[60:61], v[218:219], v[188:189]
	v_pk_fma_f32 v[62:63], v[62:63], v[220:221], v[190:191]
	v_pk_fma_f32 v[56:57], v[56:57], v[222:223], v[192:193]
	v_pk_fma_f32 v[58:59], v[58:59], v[224:225], v[194:195]
	v_pk_fma_f32 v[52:53], v[52:53], v[226:227], v[196:197]
	v_pk_fma_f32 v[54:55], v[54:55], v[228:229], v[198:199]
	v_pk_fma_f32 v[48:49], v[48:49], v[230:231], v[200:201]
	v_pk_fma_f32 v[50:51], v[50:51], v[232:233], v[202:203]
	s_add_u32 s84, s80, 0x160000
	s_addc_u32 s85, s81, 0
	global_load_dwordx4 v[188:191], v173, s[84:85] nt
	global_load_dwordx4 v[192:195], v173, s[84:85] offset:16 nt
	global_load_dwordx4 v[196:199], v173, s[84:85] offset:512 nt
	global_load_dwordx4 v[200:203], v173, s[84:85] offset:528 nt
	v_pk_mul_f32 v[176:177], v[60:61], v[60:61]
	v_pk_fma_f32 v[176:177], v[62:63], v[62:63], v[176:177]
	v_pk_fma_f32 v[176:177], v[56:57], v[56:57], v[176:177]
	v_pk_fma_f32 v[176:177], v[58:59], v[58:59], v[176:177]
	v_pk_fma_f32 v[176:177], v[52:53], v[52:53], v[176:177]
	v_pk_fma_f32 v[176:177], v[54:55], v[54:55], v[176:177]
	v_pk_fma_f32 v[176:177], v[48:49], v[48:49], v[176:177]
	v_pk_fma_f32 v[176:177], v[50:51], v[50:51], v[176:177]
	v_add_f32_e32 v208, v176, v177
	s_waitcnt vmcnt(8)
	v_pk_fma_f32 v[44:45], v[44:45], v[218:219], v[104:105]
	v_pk_fma_f32 v[46:47], v[46:47], v[220:221], v[106:107]
	v_pk_fma_f32 v[40:41], v[40:41], v[222:223], v[108:109]
	v_pk_fma_f32 v[42:43], v[42:43], v[224:225], v[110:111]
	v_pk_fma_f32 v[36:37], v[36:37], v[226:227], v[112:113]
	v_pk_fma_f32 v[38:39], v[38:39], v[228:229], v[114:115]
	v_pk_fma_f32 v[32:33], v[32:33], v[230:231], v[120:121]
	v_pk_fma_f32 v[34:35], v[34:35], v[232:233], v[122:123]
	v_pk_mul_f32 v[176:177], v[44:45], v[44:45]
	v_pk_fma_f32 v[176:177], v[46:47], v[46:47], v[176:177]
	v_pk_fma_f32 v[176:177], v[40:41], v[40:41], v[176:177]
	v_pk_fma_f32 v[176:177], v[42:43], v[42:43], v[176:177]
	v_pk_fma_f32 v[176:177], v[36:37], v[36:37], v[176:177]
	v_pk_fma_f32 v[176:177], v[38:39], v[38:39], v[176:177]
	v_pk_fma_f32 v[176:177], v[32:33], v[32:33], v[176:177]
	v_pk_fma_f32 v[176:177], v[34:35], v[34:35], v[176:177]
	v_add_f32_e32 v209, v176, v177
	s_barrier
	s_cmp_lg_u32 s59, 0
	s_cbranch_scc1 .Lepi_a1
	s_lshl_b32 s18, s58, 6
	s_add_u32 s18, s18, 0xc000
	s_mov_b64 exec, 1
	v_mov_b32_e32 v175, s18
	v_mov_b32_e32 v255, 1
	global_atomic_add v175, v255, s[50:51]
	s_mov_b64 exec, -1
.Lepi_a1:
	s_waitcnt vmcnt(4)
	v_pk_fma_f32 v[28:29], v[28:29], v[218:219], v[234:235]
	v_pk_fma_f32 v[30:31], v[30:31], v[220:221], v[236:237]
	v_pk_fma_f32 v[24:25], v[24:25], v[222:223], v[238:239]
	v_pk_fma_f32 v[26:27], v[26:27], v[224:225], v[240:241]
	v_pk_fma_f32 v[20:21], v[20:21], v[226:227], v[242:243]
	v_pk_fma_f32 v[22:23], v[22:23], v[228:229], v[244:245]
	v_pk_fma_f32 v[16:17], v[16:17], v[230:231], v[246:247]
	v_pk_fma_f32 v[18:19], v[18:19], v[232:233], v[248:249]
	v_pk_mul_f32 v[176:177], v[28:29], v[28:29]
	v_pk_fma_f32 v[176:177], v[30:31], v[30:31], v[176:177]
	v_pk_fma_f32 v[176:177], v[24:25], v[24:25], v[176:177]
	v_pk_fma_f32 v[176:177], v[26:27], v[26:27], v[176:177]
	v_pk_fma_f32 v[176:177], v[20:21], v[20:21], v[176:177]
	v_pk_fma_f32 v[176:177], v[22:23], v[22:23], v[176:177]
	v_pk_fma_f32 v[176:177], v[16:17], v[16:17], v[176:177]
	v_pk_fma_f32 v[176:177], v[18:19], v[18:19], v[176:177]
	v_add_f32_e32 v210, v176, v177
	s_cmp_lg_u32 s59, 0
	s_cbranch_scc1 .Lepi_q1
	s_lshl_b32 s18, s58, 6
	s_add_u32 s18, s18, 0xc000
	s_mov_b64 exec, 1
	v_mov_b32_e32 v175, s18
	global_load_dword v255, v175, s[50:51] sc1
	s_mov_b64 exec, -1
.Lepi_q1:
	s_waitcnt vmcnt(0)
	s_cmp_lg_u32 s59, 0
	s_cbranch_scc1 .Lepi_p1
	s_waitcnt vmcnt(0)
	v_readfirstlane_b32 s19, v255
	s_cmp_lt_u32 s19, 8
	s_cbranch_scc0 .Lepi_p0
	s_lshl_b32 s18, s58, 6
	s_add_u32 s18, s18, 0xc000
	s_mov_b64 exec, 1
	v_mov_b32_e32 v175, s18
	s_mov_b32 vcc_lo, 0

;     __device__ __forceinline__ void operator()(AccRef acc, const Unit& u, int wr, int wc, int fr, int fq) const {
;         int row0 = u.pm * 256 + wr * 64 + fr; asm volatile("" : "+v"(row0)); int col0 = u.pn * 256 + wc * 32 + 8 * fq; asm volatile("" : "+v"(col0));
;         const float* gate = mod + (size_t)(u.pm >= 32 ? 1 : 0) * 3 * D + 2 * D + col0;
;         f32x4 gv[2][2];
; #pragma unroll
;         for (int bj = 0; bj < 2; ++bj)
; #pragma unroll
;             for (int n = 0; n < 2; ++n) gv[bj][n] = *(const f32x4*)(gate + bj * HALF + n * 4);
; #pragma unroll
;         for (int ai = 0; ai < 2; ++ai)
; #pragma unroll
;             for (int mp = 0; mp < 2; ++mp) { f32x4 xv[2][2][2];
; #pragma unroll
;                 for (int mm = 0; mm < 2; ++mm)
; #pragma unroll
;                     for (int bj = 0; bj < 2; ++bj)
; #pragma unroll
;                         for (int n = 0; n < 2; ++n) xv[mm][bj][n] = ld_nt(x + (size_t)(row0 + ai * HALF + (mp * 2 + mm) * 16) * D + col0 + bj * HALF + n * 4);
;                 __builtin_amdgcn_sched_barrier(0);
; #pragma unroll
;                 for (int mm = 0; mm < 2; ++mm) { const int m = mp * 2 + mm; const int row = row0 + ai * HALF + m * 16; const size_t o = (size_t)row * D + col0; float ss = 0.f;
; #pragma unroll
;                     for (int bj = 0; bj < 2; ++bj) { const f32x4 r0 = xv[mm][bj][0] + gv[bj][0] * acc[ai][bj][m][0], r1 = xv[mm][bj][1] + gv[bj][1] * acc[ai][bj][m][1];
;                         *(u32x4*)(xo + o + bj * HALF) = pack8h(r0, r1);
;                         ss += ((r0[0] * r0[0] + r0[1] * r0[1]) + (r0[2] * r0[2] + r0[3] * r0[3])) + ((r1[0] * r1[0] + r1[1] * r1[1]) + (r1[2] * r1[2] + r1[3] * r1[3])); }
;                     ss += __shfl_xor(ss, 16); ss += __shfl_xor(ss, 32);
;                     if (fq == 0) rowss[(size_t)row * 32 + u.pn * 4 + wc] = ss; } }
; __device__ __forceinline__ void final_rows(int gw, int lane, const f16* xo, float* out, const float* fg, const float* rowss) {
;     ...
;         for (int rr = 0; rr < 4; ++rr) { part[rr] = lane < 32 ? rowss[(size_t)(r0 + rr) * 32 + lane] : 0.f;
; #pragma unroll
;             for (int j = 0; j < 4; ++j) v[rr][j] = *(const u32x4*)(xo + (size_t)(r0 + rr) * D + 512 * j + 8 * lane); }
;         __builtin_amdgcn_sched_barrier(0);
; #pragma unroll
.Lepi_polled_w0:
	buffer_inv sc1
	s_waitcnt vmcnt(0)
	s_mov_b64 exec, -1
	s_branch .Lepi_p1
.Lepi_p0:
	buffer_inv sc1
	s_waitcnt vmcnt(0)
.Lepi_p1:
	v_pk_fma_f32 v[12:13], v[12:13], v[218:219], v[188:189]
	v_pk_fma_f32 v[14:15], v[14:15], v[220:221], v[190:191]
	v_pk_fma_f32 v[8:9], v[8:9], v[222:223], v[192:193]
	v_pk_fma_f32 v[10:11], v[10:11], v[224:225], v[194:195]
	v_pk_fma_f32 v[4:5], v[4:5], v[226:227], v[196:197]
	v_pk_fma_f32 v[6:7], v[6:7], v[228:229], v[198:199]
	v_pk_fma_f32 v[0:1], v[0:1], v[230:231], v[200:201]
	v_pk_fma_f32 v[2:3], v[2:3], v[232:233], v[202:203]
	v_pk_mul_f32 v[176:177], v[12:13], v[12:13]
	v_pk_fma_f32 v[176:177], v[14:15], v[14:15], v[176:177]
	v_pk_fma_f32 v[176:177], v[8:9], v[8:9], v[176:177]
	v_pk_fma_f32 v[176:177], v[10:11], v[10:11], v[176:177]
	v_pk_fma_f32 v[176:177], v[4:5], v[4:5], v[176:177]
	v_pk_fma_f32 v[176:177], v[6:7], v[6:7], v[176:177]
	v_pk_fma_f32 v[176:177], v[0:1], v[0:1], v[176:177]
	v_pk_fma_f32 v[176:177], v[2:3], v[2:3], v[176:177]
	v_add_f32_e32 v211, v176, v177
	s_barrier
	s_mov_b64 s[90:91], s[26:27]
	global_load_dwordx4 v[188:191], v174, s[90:91]
	global_load_dwordx4 v[192:195], v174, s[90:91] offset:16
	s_add_u32 s90, s26, 0x800
	s_addc_u32 s91, s27, 0
	global_load_dwordx4 v[196:199], v174, s[90:91]
	global_load_dwordx4 v[200:203], v174, s[90:91] offset:16
	s_add_u32 s90, s26, 0x1000
	s_addc_u32 s91, s27, 0
	global_load_dwordx4 v[104:107], v174, s[90:91]
	global_load_dwordx4 v[108:111], v174, s[90:91] offset:16
	ds_bpermute_b32 v214, v186, v207
	ds_bpermute_b32 v215, v186, v208
	ds_bpermute_b32 v216, v186, v209
	ds_bpermute_b32 v217, v186, v210
	ds_bpermute_b32 v213, v186, v211
	s_waitcnt lgkmcnt(0)
	v_add_f32_e32 v207, v207, v214
	v_add_f32_e32 v208, v208, v215
	v_add_f32_e32 v209, v209, v216
	v_add_f32_e32 v210, v210, v217
	v_add_f32_e32 v211, v211, v213
	ds_bpermute_b32 v214, v185, v207
	ds_bpermute_b32 v215, v185, v208
	ds_bpermute_b32 v216, v185, v209
	ds_bpermute_b32 v217, v185, v210
	ds_bpermute_b32 v213, v185, v211
	s_waitcnt lgkmcnt(0)
	v_add_f32_e32 v207, v207, v214
	v_add_f32_e32 v208, v208, v215
	v_add_f32_e32 v209, v209, v216
	v_add_f32_e32 v210, v210, v217
	v_add_f32_e32 v211, v211, v213
	s_and_saveexec_b64 s[20:21], s[2:3]
	s_add_u32 s90, s88, 0x1800
	s_addc_u32 s91, s89, 0
	global_store_dword v187, v207, s[90:91] sc0 sc1
	s_add_u32 s90, s88, 0x4000
	s_addc_u32 s91, s89, 0
	global_store_dword v187, v208, s[90:91] sc0 sc1
	s_add_u32 s90, s88, 0x4800
	s_addc_u32 s91, s89, 0
	global_store_dword v187, v209, s[90:91] sc0 sc1
	s_add_u32 s90, s88, 0x5000
	s_addc_u32 s91, s89, 0
	global_store_dword v187, v210, s[90:91] sc0 sc1
	s_add_u32 s90, s88, 0x5800
	s_addc_u32 s91, s89, 0
	global_store_dword v187, v211, s[90:91] sc0 sc1
	s_or_b64 exec, exec, s[20:21]
	s_waitcnt vmcnt(5)
	v_pk_add_f32 v[188:189], v[188:189], v[190:191]
	v_pk_add_f32 v[192:193], v[192:193], v[194:195]
	v_pk_add_f32 v[188:189], v[188:189], v[192:193]
	v_add_f32_e32 v188, v188, v189
	v_pk_add_f32 v[196:197], v[196:197], v[198:199]
	v_pk_add_f32 v[200:201], v[200:201], v[202:203]
	v_pk_add_f32 v[196:197], v[196:197], v[200:201]
	v_add_f32_e32 v196, v196, v197
	v_pk_add_f32 v[104:105], v[104:105], v[106:107]
	v_pk_add_f32 v[108:109], v[108:109], v[110:111]
	v_pk_add_f32 v[104:105], v[104:105], v[108:109]
	v_add_f32_e32 v104, v104, v105
	ds_bpermute_b32 v214, v186, v188
	ds_bpermute_b32 v215, v186, v196
	ds_bpermute_b32 v216, v186, v104
	s_waitcnt lgkmcnt(0)
	v_add_f32_e32 v188, v188, v214
	v_add_f32_e32 v196, v196, v215
	v_add_f32_e32 v104, v104, v216
	ds_bpermute_b32 v214, v185, v188
	ds_bpermute_b32 v215, v185, v196
	ds_bpermute_b32 v216, v185, v104
	s_waitcnt lgkmcnt(0)
	v_add_f32_e32 v188, v188, v214
	v_add_f32_e32 v196, v196, v215
	v_add_f32_e32 v104, v104, v216
	v_mov_b32_e32 v214, s95
	v_mov_b32_e32 v215, s95
	v_mov_b32_e32 v216, s95
	v_fmac_f32_e32 v214, s94, v188
	v_fmac_f32_e32 v215, s94, v196
	v_fmac_f32_e32 v216, s94, v104
	v_rsq_f32_e32 v204, v214
	v_rsq_f32_e32 v206, v215
	v_rsq_f32_e32 v208, v216
	s_nop 1
	s_cmp_lg_u32 s59, 0
	s_cbranch_scc1 .Lepi_b1
	s_waitcnt vmcnt(0)
	s_branch .Lepi_b2
;     __device__ __forceinline__ void operator()(AccRef acc, const Unit& u, int wr, int wc, int fr, int fq) const {
;         int row0 = u.pm * 256 + wr * 64 + fr; asm volatile("" : "+v"(row0)); int col0 = u.pn * 256 + wc * 32 + 8 * fq; asm volatile("" : "+v"(col0));
;         const float* gate = mod + (size_t)(u.pm >= 32 ? 1 : 0) * 3 * D + 2 * D + col0;
;         f32x4 gv[2][2];
; #pragma unroll
;         for (int bj = 0; bj < 2; ++bj)
; #pragma unroll
;             for (int n = 0; n < 2; ++n) gv[bj][n] = *(const f32x4*)(gate + bj * HALF + n * 4);
; #pragma unroll
;         for (int ai = 0; ai < 2; ++ai)
; #pragma unroll
;             for (int mp = 0; mp < 2; ++mp) { f32x4 xv[2][2][2];
; #pragma unroll
;                 for (int mm = 0; mm < 2; ++mm)
; #pragma unroll
;                     for (int bj = 0; bj < 2; ++bj)
; #pragma unroll
;                         for (int n = 0; n < 2; ++n) xv[mm][bj][n] = ld_nt(x + (size_t)(row0 + ai * HALF + (mp * 2 + mm) * 16) * D + col0 + bj * HALF + n * 4);
;                 __builtin_amdgcn_sched_barrier(0);
; #pragma unroll
;                 for (int mm = 0; mm < 2; ++mm) { const int m = mp * 2 + mm; const int row = row0 + ai * HALF + m * 16; const size_t o = (size_t)row * D + col0; float ss = 0.f;
; #pragma unroll
;                     for (int bj = 0; bj < 2; ++bj) { const f32x4 r0 = xv[mm][bj][0] + gv[bj][0] * acc[ai][bj][m][0], r1 = xv[mm][bj][1] + gv[bj][1] * acc[ai][bj][m][1];
;                         *(u32x4*)(xo + o + bj * HALF) = pack8h(r0, r1);
;                         ss += ((r0[0] * r0[0] + r0[1] * r0[1]) + (r0[2] * r0[2] + r0[3] * r0[3])) + ((r1[0] * r1[0] + r1[1] * r1[1]) + (r1[2] * r1[2] + r1[3] * r1[3])); }
;                     ss += __shfl_xor(ss, 16); ss += __shfl_xor(ss, 32);
;                     if (fq == 0) rowss[(size_t)row * 32 + u.pn * 4 + wc] = ss; } }
; __device__ __forceinline__ void final_rows(int gw, int lane, const f16* xo, float* out, const float* fg, const float* rowss) {
;     ...
;         for (int rr = 0; rr < 4; ++rr) { part[rr] = lane < 32 ? rowss[(size_t)(r0 + rr) * 32 + lane] : 0.f;
; #pragma unroll
;             for (int j = 0; j < 4; ++j) v[rr][j] = *(const u32x4*)(xo + (size_t)(r0 + rr) * D + 512 * j + 8 * lane); }
;         __builtin_amdgcn_sched_barrier(0);
; #pragma unroll
.Lepi_b1:
	s_mov_b64 s[86:87], s[82:83]
	v_pk_mul_f32 v[140:141], v[140:141], v[204:205] op_sel_hi:[1,0]
	v_pk_mul_f32 v[142:143], v[142:143], v[204:205] op_sel_hi:[1,0]
	v_pk_mul_f32 v[140:141], v[140:141], v[144:145]
	v_pk_mul_f32 v[142:143], v[142:143], v[146:147]
	v_pk_mul_f32 v[136:137], v[136:137], v[204:205] op_sel_hi:[1,0]
	v_pk_mul_f32 v[138:139], v[138:139], v[204:205] op_sel_hi:[1,0]
	v_pk_mul_f32 v[136:137], v[136:137], v[148:149]
	v_pk_mul_f32 v[138:139], v[138:139], v[150:151]
	v_pk_mul_f32 v[132:133], v[132:133], v[204:205] op_sel_hi:[1,0]
	v_pk_mul_f32 v[134:135], v[134:135], v[204:205] op_sel_hi:[1,0]
	v_pk_mul_f32 v[132:133], v[132:133], v[152:153]
	v_pk_mul_f32 v[134:135], v[134:135], v[154:155]
	v_pk_mul_f32 v[128:129], v[128:129], v[204:205] op_sel_hi:[1,0]
	v_pk_mul_f32 v[130:131], v[130:131], v[204:205] op_sel_hi:[1,0]
	v_pk_mul_f32 v[128:129], v[128:129], v[156:157]
	v_pk_mul_f32 v[130:131], v[130:131], v[158:159]
	global_store_dwordx4 v173, v[140:143], s[86:87]
	global_store_dwordx4 v173, v[136:139], s[86:87] offset:16
	global_store_dwordx4 v173, v[132:135], s[86:87] offset:512
	global_store_dwordx4 v173, v[128:131], s[86:87] offset:528
	s_add_u32 s86, s82, 0x20000
	s_addc_u32 s87, s83, 0
	v_pk_mul_f32 v[124:125], v[124:125], v[206:207] op_sel_hi:[1,0]
	v_pk_mul_f32 v[126:127], v[126:127], v[206:207] op_sel_hi:[1,0]
	v_pk_mul_f32 v[124:125], v[124:125], v[144:145]
	v_pk_mul_f32 v[126:127], v[126:127], v[146:147]
	v_pk_mul_f32 v[116:117], v[116:117], v[206:207] op_sel_hi:[1,0]
	v_pk_mul_f32 v[118:119], v[118:119], v[206:207] op_sel_hi:[1,0]
	v_pk_mul_f32 v[116:117], v[116:117], v[148:149]
	v_pk_mul_f32 v[118:119], v[118:119], v[150:151]
	v_pk_mul_f32 v[100:101], v[100:101], v[206:207] op_sel_hi:[1,0]
	v_pk_mul_f32 v[102:103], v[102:103], v[206:207] op_sel_hi:[1,0]
	v_pk_mul_f32 v[100:101], v[100:101], v[152:153]
	v_pk_mul_f32 v[102:103], v[102:103], v[154:155]
	v_pk_mul_f32 v[96:97], v[96:97], v[206:207] op_sel_hi:[1,0]
	v_pk_mul_f32 v[98:99], v[98:99], v[206:207] op_sel_hi:[1,0]
	v_pk_mul_f32 v[96:97], v[96:97], v[156:157]
	v_pk_mul_f32 v[98:99], v[98:99], v[158:159]
	global_store_dwordx4 v173, v[124:127], s[86:87]
	global_store_dwordx4 v173, v[116:119], s[86:87] offset:16
	global_store_dwordx4 v173, v[100:103], s[86:87] offset:512
	global_store_dwordx4 v173, v[96:99], s[86:87] offset:528
	s_add_u32 s86, s82, 0x40000
	s_addc_u32 s87, s83, 0
	v_pk_mul_f32 v[92:93], v[92:93], v[208:209] op_sel_hi:[1,0]
	v_pk_mul_f32 v[94:95], v[94:95], v[208:209] op_sel_hi:[1,0]
	v_pk_mul_f32 v[92:93], v[92:93], v[144:145]
	v_pk_mul_f32 v[94:95], v[94:95], v[146:147]
	v_pk_mul_f32 v[88:89], v[88:89], v[208:209] op_sel_hi:[1,0]
	v_pk_mul_f32 v[90:91], v[90:91], v[208:209] op_sel_hi:[1,0]
	v_pk_mul_f32 v[88:89], v[88:89], v[148:149]
	v_pk_mul_f32 v[90:91], v[90:91], v[150:151]
	v_pk_mul_f32 v[84:85], v[84:85], v[208:209] op_sel_hi:[1,0]
	v_pk_mul_f32 v[86:87], v[86:87], v[208:209] op_sel_hi:[1,0]
	v_pk_mul_f32 v[84:85], v[84:85], v[152:153]
	v_pk_mul_f32 v[86:87], v[86:87], v[154:155]
	v_pk_mul_f32 v[80:81], v[80:81], v[208:209] op_sel_hi:[1,0]
	v_pk_mul_f32 v[82:83], v[82:83], v[208:209] op_sel_hi:[1,0]
	v_pk_mul_f32 v[80:81], v[80:81], v[156:157]
	v_pk_mul_f32 v[82:83], v[82:83], v[158:159]
	global_store_dwordx4 v173, v[92:95], s[86:87]
	global_store_dwordx4 v173, v[88:91], s[86:87] offset:16
	global_store_dwordx4 v173, v[84:87], s[86:87] offset:512
	global_store_dwordx4 v173, v[80:83], s[86:87] offset:528
	s_waitcnt vmcnt(12)
.Lepi_b2:
	s_barrier
	s_cmp_lg_u32 s59, 0
	s_cbranch_scc1 .Lepi_c1
	s_lshl_b32 s18, s58, 6
	s_add_u32 s18, s18, 0xc020
	s_mov_b64 exec, 1
	v_mov_b32_e32 v175, s18
	v_mov_b32_e32 v255, 1
	global_atomic_add v175, v255, s[50:51]
	s_mov_b64 exec, -1
	s_waitcnt vmcnt(0)
	s_lshl_b32 s18, s58, 6
	s_add_u32 s18, s18, 0xc020
	s_mov_b64 exec, 1
	v_mov_b32_e32 v175, s18
	s_mov_b32 vcc_lo, 0

;     __device__ __forceinline__ void operator()(AccRef acc, const Unit& u, int wr, int wc, int fr, int fq) const {
;         int row0 = u.pm * 256 + wr * 64 + fr; asm volatile("" : "+v"(row0)); int col0 = u.pn * 256 + wc * 32 + 8 * fq; asm volatile("" : "+v"(col0));
;         const float* gate = mod + (size_t)(u.pm >= 32 ? 1 : 0) * 3 * D + 2 * D + col0;
;         f32x4 gv[2][2];
; #pragma unroll
;         for (int bj = 0; bj < 2; ++bj)
; #pragma unroll
;             for (int n = 0; n < 2; ++n) gv[bj][n] = *(const f32x4*)(gate + bj * HALF + n * 4);
; #pragma unroll
;         for (int ai = 0; ai < 2; ++ai)
; #pragma unroll
;             for (int mp = 0; mp < 2; ++mp) { f32x4 xv[2][2][2];
; #pragma unroll
;                 for (int mm = 0; mm < 2; ++mm)
; #pragma unroll
;                     for (int bj = 0; bj < 2; ++bj)
; #pragma unroll
;                         for (int n = 0; n < 2; ++n) xv[mm][bj][n] = ld_nt(x + (size_t)(row0 + ai * HALF + (mp * 2 + mm) * 16) * D + col0 + bj * HALF + n * 4);
;                 __builtin_amdgcn_sched_barrier(0);
; #pragma unroll
;                 for (int mm = 0; mm < 2; ++mm) { const int m = mp * 2 + mm; const int row = row0 + ai * HALF + m * 16; const size_t o = (size_t)row * D + col0; float ss = 0.f;
; #pragma unroll
;                     for (int bj = 0; bj < 2; ++bj) { const f32x4 r0 = xv[mm][bj][0] + gv[bj][0] * acc[ai][bj][m][0], r1 = xv[mm][bj][1] + gv[bj][1] * acc[ai][bj][m][1];
;                         *(u32x4*)(xo + o + bj * HALF) = pack8h(r0, r1);
;                         ss += ((r0[0] * r0[0] + r0[1] * r0[1]) + (r0[2] * r0[2] + r0[3] * r0[3])) + ((r1[0] * r1[0] + r1[1] * r1[1]) + (r1[2] * r1[2] + r1[3] * r1[3])); }
;                     ss += __shfl_xor(ss, 16); ss += __shfl_xor(ss, 32);
;                     if (fq == 0) rowss[(size_t)row * 32 + u.pn * 4 + wc] = ss; } }
; __device__ __forceinline__ void final_rows(int gw, int lane, const f16* xo, float* out, const float* fg, const float* rowss) {
;     ...
;         for (int rr = 0; rr < 4; ++rr) { part[rr] = lane < 32 ? rowss[(size_t)(r0 + rr) * 32 + lane] : 0.f;
; #pragma unroll
;             for (int j = 0; j < 4; ++j) v[rr][j] = *(const u32x4*)(xo + (size_t)(r0 + rr) * D + 512 * j + 8 * lane); }
;         __builtin_amdgcn_sched_barrier(0);
; #pragma unroll
.Lepi_c1:
	s_barrier
	s_add_u32 s90, s26, 0x1800
	s_addc_u32 s91, s27, 0
	global_load_dwordx4 v[188:191], v174, s[90:91]
	global_load_dwordx4 v[192:195], v174, s[90:91] offset:16
	s_add_u32 s90, s26, 0x4000
	s_addc_u32 s91, s27, 0
	global_load_dwordx4 v[196:199], v174, s[90:91]
	global_load_dwordx4 v[200:203], v174, s[90:91] offset:16
	s_add_u32 s90, s26, 0x4800
	s_addc_u32 s91, s27, 0
	global_load_dwordx4 v[104:107], v174, s[90:91]
	global_load_dwordx4 v[108:111], v174, s[90:91] offset:16
	s_add_u32 s90, s26, 0x5000
	s_addc_u32 s91, s27, 0
	global_load_dwordx4 v[112:115], v174, s[90:91]
	global_load_dwordx4 v[120:123], v174, s[90:91] offset:16
	s_add_u32 s90, s26, 0x5800
	s_addc_u32 s91, s27, 0
	global_load_dwordx4 v[234:237], v174, s[90:91]
	global_load_dwordx4 v[238:241], v174, s[90:91] offset:16
	s_cmp_lg_u32 s59, 0
	s_cbranch_scc1 .Lepi_e1
	s_mov_b64 s[86:87], s[82:83]
	v_pk_mul_f32 v[140:141], v[140:141], v[204:205] op_sel_hi:[1,0]
	v_pk_mul_f32 v[142:143], v[142:143], v[204:205] op_sel_hi:[1,0]
	v_pk_mul_f32 v[140:141], v[140:141], v[144:145]
	v_pk_mul_f32 v[142:143], v[142:143], v[146:147]
	v_pk_mul_f32 v[136:137], v[136:137], v[204:205] op_sel_hi:[1,0]
	v_pk_mul_f32 v[138:139], v[138:139], v[204:205] op_sel_hi:[1,0]
	v_pk_mul_f32 v[136:137], v[136:137], v[148:149]
	v_pk_mul_f32 v[138:139], v[138:139], v[150:151]
	v_pk_mul_f32 v[132:133], v[132:133], v[204:205] op_sel_hi:[1,0]
	v_pk_mul_f32 v[134:135], v[134:135], v[204:205] op_sel_hi:[1,0]
	v_pk_mul_f32 v[132:133], v[132:133], v[152:153]
	v_pk_mul_f32 v[134:135], v[134:135], v[154:155]
	v_pk_mul_f32 v[128:129], v[128:129], v[204:205] op_sel_hi:[1,0]
	v_pk_mul_f32 v[130:131], v[130:131], v[204:205] op_sel_hi:[1,0]
	v_pk_mul_f32 v[128:129], v[128:129], v[156:157]
	v_pk_mul_f32 v[130:131], v[130:131], v[158:159]
	global_store_dwordx4 v173, v[140:143], s[86:87]
	global_store_dwordx4 v173, v[136:139], s[86:87] offset:16
	global_store_dwordx4 v173, v[132:135], s[86:87] offset:512
	global_store_dwordx4 v173, v[128:131], s[86:87] offset:528
	s_add_u32 s86, s82, 0x20000
	s_addc_u32 s87, s83, 0
	v_pk_mul_f32 v[124:125], v[124:125], v[206:207] op_sel_hi:[1,0]
	v_pk_mul_f32 v[126:127], v[126:127], v[206:207] op_sel_hi:[1,0]
	v_pk_mul_f32 v[124:125], v[124:125], v[144:145]
	v_pk_mul_f32 v[126:127], v[126:127], v[146:147]
	v_pk_mul_f32 v[116:117], v[116:117], v[206:207] op_sel_hi:[1,0]
	v_pk_mul_f32 v[118:119], v[118:119], v[206:207] op_sel_hi:[1,0]
	v_pk_mul_f32 v[116:117], v[116:117], v[148:149]
	v_pk_mul_f32 v[118:119], v[118:119], v[150:151]
	v_pk_mul_f32 v[100:101], v[100:101], v[206:207] op_sel_hi:[1,0]
	v_pk_mul_f32 v[102:103], v[102:103], v[206:207] op_sel_hi:[1,0]
	v_pk_mul_f32 v[100:101], v[100:101], v[152:153]
	v_pk_mul_f32 v[102:103], v[102:103], v[154:155]
	v_pk_mul_f32 v[96:97], v[96:97], v[206:207] op_sel_hi:[1,0]
	v_pk_mul_f32 v[98:99], v[98:99], v[206:207] op_sel_hi:[1,0]
	v_pk_mul_f32 v[96:97], v[96:97], v[156:157]
	v_pk_mul_f32 v[98:99], v[98:99], v[158:159]
	global_store_dwordx4 v173, v[124:127], s[86:87]
	global_store_dwordx4 v173, v[116:119], s[86:87] offset:16
	global_store_dwordx4 v173, v[100:103], s[86:87] offset:512
	global_store_dwordx4 v173, v[96:99], s[86:87] offset:528
	s_add_u32 s86, s82, 0x40000
	s_addc_u32 s87, s83, 0
	v_pk_mul_f32 v[92:93], v[92:93], v[208:209] op_sel_hi:[1,0]
	v_pk_mul_f32 v[94:95], v[94:95], v[208:209] op_sel_hi:[1,0]
	v_pk_mul_f32 v[92:93], v[92:93], v[144:145]
	v_pk_mul_f32 v[94:95], v[94:95], v[146:147]
	v_pk_mul_f32 v[88:89], v[88:89], v[208:209] op_sel_hi:[1,0]
	v_pk_mul_f32 v[90:91], v[90:91], v[208:209] op_sel_hi:[1,0]
	v_pk_mul_f32 v[88:89], v[88:89], v[148:149]
	v_pk_mul_f32 v[90:91], v[90:91], v[150:151]
	v_pk_mul_f32 v[84:85], v[84:85], v[208:209] op_sel_hi:[1,0]
	v_pk_mul_f32 v[86:87], v[86:87], v[208:209] op_sel_hi:[1,0]
	v_pk_mul_f32 v[84:85], v[84:85], v[152:153]
	v_pk_mul_f32 v[86:87], v[86:87], v[154:155]
	v_pk_mul_f32 v[80:81], v[80:81], v[208:209] op_sel_hi:[1,0]
	v_pk_mul_f32 v[82:83], v[82:83], v[208:209] op_sel_hi:[1,0]
	v_pk_mul_f32 v[80:81], v[80:81], v[156:157]
	v_pk_mul_f32 v[82:83], v[82:83], v[158:159]
	global_store_dwordx4 v173, v[92:95], s[86:87]
	global_store_dwordx4 v173, v[88:91], s[86:87] offset:16
	global_store_dwordx4 v173, v[84:87], s[86:87] offset:512
	global_store_dwordx4 v173, v[80:83], s[86:87] offset:528
	s_waitcnt vmcnt(12)
	s_branch .Lepi_e2

;     __device__ __forceinline__ void operator()(AccRef acc, const Unit& u, int wr, int wc, int fr, int fq) const {
;         int row0 = u.pm * 256 + wr * 64 + fr; asm volatile("" : "+v"(row0)); int col0 = u.pn * 256 + wc * 32 + 8 * fq; asm volatile("" : "+v"(col0));
;         const float* gate = mod + (size_t)(u.pm >= 32 ? 1 : 0) * 3 * D + 2 * D + col0;
;         f32x4 gv[2][2];
; #pragma unroll
;         for (int bj = 0; bj < 2; ++bj)
; #pragma unroll
;             for (int n = 0; n < 2; ++n) gv[bj][n] = *(const f32x4*)(gate + bj * HALF + n * 4);
; #pragma unroll
;         for (int ai = 0; ai < 2; ++ai)
; #pragma unroll
;             for (int mp = 0; mp < 2; ++mp) { f32x4 xv[2][2][2];
; #pragma unroll
;                 for (int mm = 0; mm < 2; ++mm)
; #pragma unroll
;                     for (int bj = 0; bj < 2; ++bj)
; #pragma unroll
;                         for (int n = 0; n < 2; ++n) xv[mm][bj][n] = ld_nt(x + (size_t)(row0 + ai * HALF + (mp * 2 + mm) * 16) * D + col0 + bj * HALF + n * 4);
;                 __builtin_amdgcn_sched_barrier(0);
; #pragma unroll
;                 for (int mm = 0; mm < 2; ++mm) { const int m = mp * 2 + mm; const int row = row0 + ai * HALF + m * 16; const size_t o = (size_t)row * D + col0; float ss = 0.f;
; #pragma unroll
;                     for (int bj = 0; bj < 2; ++bj) { const f32x4 r0 = xv[mm][bj][0] + gv[bj][0] * acc[ai][bj][m][0], r1 = xv[mm][bj][1] + gv[bj][1] * acc[ai][bj][m][1];
;                         *(u32x4*)(xo + o + bj * HALF) = pack8h(r0, r1);
;                         ss += ((r0[0] * r0[0] + r0[1] * r0[1]) + (r0[2] * r0[2] + r0[3] * r0[3])) + ((r1[0] * r1[0] + r1[1] * r1[1]) + (r1[2] * r1[2] + r1[3] * r1[3])); }
;                     ss += __shfl_xor(ss, 16); ss += __shfl_xor(ss, 32);
;                     if (fq == 0) rowss[(size_t)row * 32 + u.pn * 4 + wc] = ss; } }
; __device__ __forceinline__ void final_rows(int gw, int lane, const f16* xo, float* out, const float* fg, const float* rowss) {
;     ...
;         for (int rr = 0; rr < 4; ++rr) { part[rr] = lane < 32 ? rowss[(size_t)(r0 + rr) * 32 + lane] : 0.f;
; #pragma unroll
;             for (int j = 0; j < 4; ++j) v[rr][j] = *(const u32x4*)(xo + (size_t)(r0 + rr) * D + 512 * j + 8 * lane); }
;         __builtin_amdgcn_sched_barrier(0);
; #pragma unroll
.Lepi_e2:
	v_pk_add_f32 v[188:189], v[188:189], v[190:191]
	v_pk_add_f32 v[192:193], v[192:193], v[194:195]
	v_pk_add_f32 v[188:189], v[188:189], v[192:193]
	v_add_f32_e32 v188, v188, v189
	v_pk_add_f32 v[196:197], v[196:197], v[198:199]
	v_pk_add_f32 v[200:201], v[200:201], v[202:203]
	v_pk_add_f32 v[196:197], v[196:197], v[200:201]
	v_add_f32_e32 v196, v196, v197
	v_pk_add_f32 v[104:105], v[104:105], v[106:107]
	v_pk_add_f32 v[108:109], v[108:109], v[110:111]
	v_pk_add_f32 v[104:105], v[104:105], v[108:109]
	v_add_f32_e32 v104, v104, v105
	v_pk_add_f32 v[112:113], v[112:113], v[114:115]
	v_pk_add_f32 v[120:121], v[120:121], v[122:123]
	v_pk_add_f32 v[112:113], v[112:113], v[120:121]
	v_add_f32_e32 v112, v112, v113
	v_pk_add_f32 v[234:235], v[234:235], v[236:237]
	v_pk_add_f32 v[238:239], v[238:239], v[240:241]
	v_pk_add_f32 v[234:235], v[234:235], v[238:239]
	v_add_f32_e32 v234, v234, v235
	ds_bpermute_b32 v214, v186, v188
	ds_bpermute_b32 v215, v186, v196
	ds_bpermute_b32 v216, v186, v104
	ds_bpermute_b32 v217, v186, v112
	ds_bpermute_b32 v213, v186, v234
	s_waitcnt lgkmcnt(0)
	v_add_f32_e32 v188, v188, v214
	v_add_f32_e32 v196, v196, v215
	v_add_f32_e32 v104, v104, v216
	v_add_f32_e32 v112, v112, v217
	v_add_f32_e32 v234, v234, v213
	ds_bpermute_b32 v214, v185, v188
	ds_bpermute_b32 v215, v185, v196
	ds_bpermute_b32 v216, v185, v104
	ds_bpermute_b32 v217, v185, v112
	ds_bpermute_b32 v213, v185, v234
	s_waitcnt lgkmcnt(0)
	v_add_f32_e32 v188, v188, v214
	v_add_f32_e32 v196, v196, v215
	v_add_f32_e32 v104, v104, v216
	v_add_f32_e32 v112, v112, v217
	v_add_f32_e32 v234, v234, v213
	v_mov_b32_e32 v214, s95
	v_mov_b32_e32 v215, s95
	v_mov_b32_e32 v216, s95
	v_mov_b32_e32 v217, s95
	v_mov_b32_e32 v213, s95
	v_fmac_f32_e32 v214, s94, v188
	v_fmac_f32_e32 v215, s94, v196
	v_fmac_f32_e32 v216, s94, v104
	v_fmac_f32_e32 v217, s94, v112
	v_fmac_f32_e32 v213, s94, v234
	v_rsq_f32_e32 v204, v214
	v_rsq_f32_e32 v206, v215
	v_rsq_f32_e32 v208, v216
	v_rsq_f32_e32 v210, v217
	v_rsq_f32_e32 v250, v213
	s_nop 1
	s_add_u32 s86, s82, 0x60000
	s_addc_u32 s87, s83, 0
	v_pk_mul_f32 v[76:77], v[76:77], v[204:205] op_sel_hi:[1,0]
	v_pk_mul_f32 v[78:79], v[78:79], v[204:205] op_sel_hi:[1,0]
	v_pk_mul_f32 v[76:77], v[76:77], v[144:145]
	v_pk_mul_f32 v[78:79], v[78:79], v[146:147]
	v_pk_mul_f32 v[72:73], v[72:73], v[204:205] op_sel_hi:[1,0]
	v_pk_mul_f32 v[74:75], v[74:75], v[204:205] op_sel_hi:[1,0]
	v_pk_mul_f32 v[72:73], v[72:73], v[148:149]
	v_pk_mul_f32 v[74:75], v[74:75], v[150:151]
	v_pk_mul_f32 v[68:69], v[68:69], v[204:205] op_sel_hi:[1,0]
	v_pk_mul_f32 v[70:71], v[70:71], v[204:205] op_sel_hi:[1,0]
	v_pk_mul_f32 v[68:69], v[68:69], v[152:153]
	v_pk_mul_f32 v[70:71], v[70:71], v[154:155]
	v_pk_mul_f32 v[64:65], v[64:65], v[204:205] op_sel_hi:[1,0]
	v_pk_mul_f32 v[66:67], v[66:67], v[204:205] op_sel_hi:[1,0]
	v_pk_mul_f32 v[64:65], v[64:65], v[156:157]
	v_pk_mul_f32 v[66:67], v[66:67], v[158:159]
	global_store_dwordx4 v173, v[76:79], s[86:87]
	global_store_dwordx4 v173, v[72:75], s[86:87] offset:16
	global_store_dwordx4 v173, v[68:71], s[86:87] offset:512
	global_store_dwordx4 v173, v[64:67], s[86:87] offset:528
	s_add_u32 s86, s82, 0x100000
	s_addc_u32 s87, s83, 0
	v_pk_mul_f32 v[60:61], v[60:61], v[206:207] op_sel_hi:[1,0]
	v_pk_mul_f32 v[62:63], v[62:63], v[206:207] op_sel_hi:[1,0]
	v_pk_mul_f32 v[60:61], v[60:61], v[144:145]
	v_pk_mul_f32 v[62:63], v[62:63], v[146:147]
	v_pk_mul_f32 v[56:57], v[56:57], v[206:207] op_sel_hi:[1,0]
	v_pk_mul_f32 v[58:59], v[58:59], v[206:207] op_sel_hi:[1,0]
	v_pk_mul_f32 v[56:57], v[56:57], v[148:149]
	v_pk_mul_f32 v[58:59], v[58:59], v[150:151]
	v_pk_mul_f32 v[52:53], v[52:53], v[206:207] op_sel_hi:[1,0]
	v_pk_mul_f32 v[54:55], v[54:55], v[206:207] op_sel_hi:[1,0]
	v_pk_mul_f32 v[52:53], v[52:53], v[152:153]
	v_pk_mul_f32 v[54:55], v[54:55], v[154:155]
	v_pk_mul_f32 v[48:49], v[48:49], v[206:207] op_sel_hi:[1,0]
	v_pk_mul_f32 v[50:51], v[50:51], v[206:207] op_sel_hi:[1,0]
	v_pk_mul_f32 v[48:49], v[48:49], v[156:157]
	v_pk_mul_f32 v[50:51], v[50:51], v[158:159]
	global_store_dwordx4 v173, v[60:63], s[86:87]
	global_store_dwordx4 v173, v[56:59], s[86:87] offset:16
	global_store_dwordx4 v173, v[52:55], s[86:87] offset:512
	global_store_dwordx4 v173, v[48:51], s[86:87] offset:528
;     __device__ __forceinline__ void operator()(AccRef acc, const Unit& u, int wr, int wc, int fr, int fq) const {
;         int row0 = u.pm * 256 + wr * 64 + fr; asm volatile("" : "+v"(row0)); int col0 = u.pn * 256 + wc * 32 + 8 * fq; asm volatile("" : "+v"(col0));
;         const float* gate = mod + (size_t)(u.pm >= 32 ? 1 : 0) * 3 * D + 2 * D + col0;
;         f32x4 gv[2][2];
; #pragma unroll
;         for (int bj = 0; bj < 2; ++bj)
; #pragma unroll
;             for (int n = 0; n < 2; ++n) gv[bj][n] = *(const f32x4*)(gate + bj * HALF + n * 4);
; #pragma unroll
;         for (int ai = 0; ai < 2; ++ai)
; #pragma unroll
;             for (int mp = 0; mp < 2; ++mp) { f32x4 xv[2][2][2];
; #pragma unroll
;                 for (int mm = 0; mm < 2; ++mm)
; #pragma unroll
;                     for (int bj = 0; bj < 2; ++bj)
; #pragma unroll
;                         for (int n = 0; n < 2; ++n) xv[mm][bj][n] = ld_nt(x + (size_t)(row0 + ai * HALF + (mp * 2 + mm) * 16) * D + col0 + bj * HALF + n * 4);
;                 __builtin_amdgcn_sched_barrier(0);
; #pragma unroll
;                 for (int mm = 0; mm < 2; ++mm) { const int m = mp * 2 + mm; const int row = row0 + ai * HALF + m * 16; const size_t o = (size_t)row * D + col0; float ss = 0.f;
; #pragma unroll
;                     for (int bj = 0; bj < 2; ++bj) { const f32x4 r0 = xv[mm][bj][0] + gv[bj][0] * acc[ai][bj][m][0], r1 = xv[mm][bj][1] + gv[bj][1] * acc[ai][bj][m][1];
;                         *(u32x4*)(xo + o + bj * HALF) = pack8h(r0, r1);
;                         ss += ((r0[0] * r0[0] + r0[1] * r0[1]) + (r0[2] * r0[2] + r0[3] * r0[3])) + ((r1[0] * r1[0] + r1[1] * r1[1]) + (r1[2] * r1[2] + r1[3] * r1[3])); }
;                     ss += __shfl_xor(ss, 16); ss += __shfl_xor(ss, 32);
;                     if (fq == 0) rowss[(size_t)row * 32 + u.pn * 4 + wc] = ss; } }
; __device__ __forceinline__ void final_rows(int gw, int lane, const f16* xo, float* out, const float* fg, const float* rowss) {
;     ...
;         for (int rr = 0; rr < 4; ++rr) { part[rr] = lane < 32 ? rowss[(size_t)(r0 + rr) * 32 + lane] : 0.f;
; #pragma unroll
;             for (int j = 0; j < 4; ++j) v[rr][j] = *(const u32x4*)(xo + (size_t)(r0 + rr) * D + 512 * j + 8 * lane); }
;         __builtin_amdgcn_sched_barrier(0);
; #pragma unroll
	s_add_u32 s86, s82, 0x120000
	s_addc_u32 s87, s83, 0
	v_pk_mul_f32 v[44:45], v[44:45], v[208:209] op_sel_hi:[1,0]
	v_pk_mul_f32 v[46:47], v[46:47], v[208:209] op_sel_hi:[1,0]
	v_pk_mul_f32 v[44:45], v[44:45], v[144:145]
	v_pk_mul_f32 v[46:47], v[46:47], v[146:147]
	v_pk_mul_f32 v[40:41], v[40:41], v[208:209] op_sel_hi:[1,0]
	v_pk_mul_f32 v[42:43], v[42:43], v[208:209] op_sel_hi:[1,0]
	v_pk_mul_f32 v[40:41], v[40:41], v[148:149]
	v_pk_mul_f32 v[42:43], v[42:43], v[150:151]
	v_pk_mul_f32 v[36:37], v[36:37], v[208:209] op_sel_hi:[1,0]
	v_pk_mul_f32 v[38:39], v[38:39], v[208:209] op_sel_hi:[1,0]
	v_pk_mul_f32 v[36:37], v[36:37], v[152:153]
	v_pk_mul_f32 v[38:39], v[38:39], v[154:155]
	v_pk_mul_f32 v[32:33], v[32:33], v[208:209] op_sel_hi:[1,0]
	v_pk_mul_f32 v[34:35], v[34:35], v[208:209] op_sel_hi:[1,0]
	v_pk_mul_f32 v[32:33], v[32:33], v[156:157]
	v_pk_mul_f32 v[34:35], v[34:35], v[158:159]
	global_store_dwordx4 v173, v[44:47], s[86:87]
	global_store_dwordx4 v173, v[40:43], s[86:87] offset:16
	global_store_dwordx4 v173, v[36:39], s[86:87] offset:512
	global_store_dwordx4 v173, v[32:35], s[86:87] offset:528
	s_add_u32 s86, s82, 0x140000
	s_addc_u32 s87, s83, 0
	v_pk_mul_f32 v[28:29], v[28:29], v[210:211] op_sel_hi:[1,0]
	v_pk_mul_f32 v[30:31], v[30:31], v[210:211] op_sel_hi:[1,0]
	v_pk_mul_f32 v[28:29], v[28:29], v[144:145]
	v_pk_mul_f32 v[30:31], v[30:31], v[146:147]
	v_pk_mul_f32 v[24:25], v[24:25], v[210:211] op_sel_hi:[1,0]
	v_pk_mul_f32 v[26:27], v[26:27], v[210:211] op_sel_hi:[1,0]
	v_pk_mul_f32 v[24:25], v[24:25], v[148:149]
	v_pk_mul_f32 v[26:27], v[26:27], v[150:151]
	v_pk_mul_f32 v[20:21], v[20:21], v[210:211] op_sel_hi:[1,0]
	v_pk_mul_f32 v[22:23], v[22:23], v[210:211] op_sel_hi:[1,0]
	v_pk_mul_f32 v[20:21], v[20:21], v[152:153]
	v_pk_mul_f32 v[22:23], v[22:23], v[154:155]
	v_pk_mul_f32 v[16:17], v[16:17], v[210:211] op_sel_hi:[1,0]
	v_pk_mul_f32 v[18:19], v[18:19], v[210:211] op_sel_hi:[1,0]
	v_pk_mul_f32 v[16:17], v[16:17], v[156:157]
	v_pk_mul_f32 v[18:19], v[18:19], v[158:159]
	global_store_dwordx4 v173, v[28:31], s[86:87]
	global_store_dwordx4 v173, v[24:27], s[86:87] offset:16
	global_store_dwordx4 v173, v[20:23], s[86:87] offset:512
	global_store_dwordx4 v173, v[16:19], s[86:87] offset:528
	s_add_u32 s86, s82, 0x160000
	s_addc_u32 s87, s83, 0
	v_pk_mul_f32 v[12:13], v[12:13], v[250:251] op_sel_hi:[1,0]
	v_pk_mul_f32 v[14:15], v[14:15], v[250:251] op_sel_hi:[1,0]
	v_pk_mul_f32 v[12:13], v[12:13], v[144:145]
	v_pk_mul_f32 v[14:15], v[14:15], v[146:147]
	v_pk_mul_f32 v[8:9], v[8:9], v[250:251] op_sel_hi:[1,0]
	v_pk_mul_f32 v[10:11], v[10:11], v[250:251] op_sel_hi:[1,0]
	v_pk_mul_f32 v[8:9], v[8:9], v[148:149]
	v_pk_mul_f32 v[10:11], v[10:11], v[150:151]
	v_pk_mul_f32 v[4:5], v[4:5], v[250:251] op_sel_hi:[1,0]
	v_pk_mul_f32 v[6:7], v[6:7], v[250:251] op_sel_hi:[1,0]
	v_pk_mul_f32 v[4:5], v[4:5], v[152:153]
	v_pk_mul_f32 v[6:7], v[6:7], v[154:155]
	v_pk_mul_f32 v[0:1], v[0:1], v[250:251] op_sel_hi:[1,0]
	v_pk_mul_f32 v[2:3], v[2:3], v[250:251] op_sel_hi:[1,0]
	v_pk_mul_f32 v[0:1], v[0:1], v[156:157]
	v_pk_mul_f32 v[2:3], v[2:3], v[158:159]
	global_store_dwordx4 v173, v[12:15], s[86:87]
	global_store_dwordx4 v173, v[8:11], s[86:87] offset:16
	global_store_dwordx4 v173, v[4:7], s[86:87] offset:512
	global_store_dwordx4 v173, v[0:3], s[86:87] offset:528
	s_and_b64 vcc, exec, s[4:5]
	s_cbranch_vccz .Lepi_nopre
	v_lshl_add_u32 v250, s44, 8, v178
	v_lshl_or_b32 v251, s42, 8, v180
	v_readlane_b32 s98, v254, 2
	v_readlane_b32 s99, v254, 3
	v_lshlrev_b32_e32 v250, 13, v250
	v_lshlrev_b32_e32 v251, 2, v251
	s_cmp_gt_i32 s44, 31
	s_cselect_b32 vcc_lo, 0x6000, 0
	s_add_u32 s100, s50, vcc_lo
	s_addc_u32 s101, s51, 0
	s_add_u32 s100, s100, 0x104000
	s_addc_u32 s101, s101, 0
	v_add_u32_e32 v250, v250, v251
	s_nop 1
	global_load_dwordx4 v[218:221], v251, s[100:101]
	global_load_dwordx4 v[222:225], v251, s[100:101] offset:16
	global_load_dwordx4 v[226:229], v251, s[100:101] offset:512
	global_load_dwordx4 v[230:233], v251, s[100:101] offset:528
	global_load_dwordx4 v[234:237], v250, s[98:99] nt
	global_load_dwordx4 v[238:241], v250, s[98:99] offset:16 nt
	global_load_dwordx4 v[242:245], v250, s[98:99] offset:512 nt
	global_load_dwordx4 v[246:249], v250, s[98:99] offset:528 nt
